# nsa_wg: one static s_setprio 1 for waves 4-7 for the whole attention part, per-tile priority flips deleted, reset at phase end
# baseline (speedup 1.0000x reference)
.LBB0_2298:
	v_readfirstlane_b32 s0, v0
	s_nop 3
	s_and_b32 s0, s0, 0x3ff
	s_lshr_b32 s0, s0, 6
	s_cmp_ge_u32 s0, 4
	s_cbranch_scc0 .Lnsa_prio_done
	s_setprio 1

.LBB0_3132:
.LBB0_3133:
	s_setprio 0
	s_cmp_gt_i32 s35, 15
	s_cselect_b64 s[0:1], -1, 0
	s_and_b64 s[4:5], s[80:81], s[0:1]
	s_andn2_b64 vcc, exec, s[4:5]
	s_cbranch_vccnz .LBB0_3183
	s_waitcnt vmcnt(0)
	v_cmp_eq_u32_e32 vcc, 0, v0
	s_waitcnt vmcnt(0) lgkmcnt(0)
	s_barrier
	s_and_saveexec_b64 s[4:5], vcc
	s_cbranch_execz .LBB0_3182
	v_mov_b32_e32 v1, s96
	s_waitcnt vmcnt(0) expcnt(0) lgkmcnt(0)
	ds_read_b32 v3, v1
	ds_read_b32 v1, v1 offset:4
	s_waitcnt lgkmcnt(1)
	v_cmp_ne_u32_e32 vcc, 0, v3
	s_cbranch_vccnz .LBB0_3150
	v_readlane_b32 s6, v254, 0
	v_readlane_b32 s7, v254, 1
	s_load_dwordx2 s[10:11], s[6:7], 0x4
	s_add_u32 s6, s30, 0x4200
	s_addc_u32 s7, s31, 0
	s_add_u32 s8, s30, 0x4400
	s_addc_u32 s9, s31, 0
	s_waitcnt lgkmcnt(0)
	s_mul_i32 s3, s10, s90
	s_add_u32 s10, s30, 0x4500
	s_mul_i32 s3, s3, s11
	s_addc_u32 s11, s31, 0
	s_add_u32 s12, s30, 0x4600
	s_addc_u32 s13, s31, 0
	s_add_u32 s14, s30, 0x4700
	s_addc_u32 s15, s31, 0
	s_add_u32 s16, s30, 0x4800
	s_addc_u32 s17, s31, 0
	s_add_u32 s18, s30, 0x4900
	s_addc_u32 s19, s31, 0
	s_add_u32 s20, s30, 0x4a00
	s_addc_u32 s21, s31, 0
	s_add_u32 s22, s30, 0x4b00
	s_addc_u32 s23, s31, 0
	s_add_u32 s46, s30, 0x4c00
	s_addc_u32 s47, s31, 0
	s_add_u32 s48, s30, 0x4d00
	s_addc_u32 s49, s31, 0
	s_add_u32 s50, s30, 0x4e00
	s_addc_u32 s51, s31, 0
	s_add_u32 s52, s30, 0x4f00
	s_addc_u32 s53, s31, 0
	s_add_u32 s54, s30, 0x5000
	s_addc_u32 s55, s31, 0
	s_add_u32 s56, s30, 0x5100
	s_addc_u32 s57, s31, 0
	s_add_u32 s58, s30, 0x5200
	s_addc_u32 s59, s31, 0
	s_add_u32 s60, s30, 0x5300
	s_addc_u32 s61, s31, 0
	s_mov_b32 s24, 1
	v_mov_b32_e32 v17, 0
	s_branch .LBB0_3138
